# MoBA tile body rewritten (bias folded into MFMA C, max3 tree, permlane32 exchange, lazy O rescale, exp/PV interleave); scan compute loop without spurious vmcnt waits + setprio
# speedup vs baseline: 1.0092x; 1.0092x over previous
; #define LAS __attribute__((address_space(3)))
; #define MFMA16(a, b, c) __builtin_amdgcn_mfma_f32_16x16x32_bf16((a), (b), (c), 0, 0, 0)
; __device__ __forceinline__ bf16x8 pack44(const f32x4 a, const f32x4 b) { u32x4 w = {pkbf(a[0], a[1]), pkbf(a[2], a[3]), pkbf(b[0], b[1]), pkbf(b[2], b[3])}; return __builtin_bit_cast(bf16x8, w); }
; __device__ __forceinline__ void phase_dn_scan3(const Params& p, LAS unsigned char* lds) {
;     ...
;             f32x4 S[8];
; #pragma unroll
;             for (int dt = 0; dt < 8; ++dt) S[dt] = (f32x4){0.f, 0.f, 0.f, 0.f};
;             SC_BAR();
; #pragma unroll 1
;             for (int n = 0; n < 64; ++n) {
;                 const LAS unsigned char* bp = lds + (n & 1) * BUF;
;                 const LAS unsigned char* wr_ = bp + O_W + i16 * WP + 8 * g4;
;                 const LAS unsigned char* qr_ = bp + O_Q + i16 * WP + 8 * g4;
;                 const LAS unsigned char* qkr = bp + O_QK + i16 * QP + 8 * g4;
;                 const LAS unsigned char* ktr = bp + O_KT + i16 * KP + 8 * g4;
;                 const LAS unsigned char* ur = bp + O_U + (4 * g4) * UP + (wave * 16 + i16) * 2;
;                 const LAS float* gcl = (const LAS float*)(bp + O_GC) + 4 * g4;
;                 const float gl = ((const LAS float*)(bp + O_GC))[63];
;                 bf16_t* uo = QKV + (rowb + n * 64 + 4 * g4) * 6144 + 4096 + h * 128 + dvq * 32 + wave * 16 + i16;
;                 bf16x8 wf[4][4], qf4[4][4];
; #pragma unroll
;                 for (int mt = 0; mt < 4; ++mt)
; #pragma unroll
;                     for (int kc = 0; kc < 4; ++kc) { wf[mt][kc] = ldl44(wr_ + 16 * mt * WP + 64 * kc); qf4[mt][kc] = ldl44(qr_ + 16 * mt * WP + 64 * kc); }
;                 asm volatile("" ::: "memory");
;                 bf16x8 sb[4];
; #pragma unroll
;                 for (int kc = 0; kc < 4; ++kc) sb[kc] = pack44(S[2 * kc], S[2 * kc + 1]);
;                 f32x4 ws4[4], qs4[4];
; #pragma unroll
;                 for (int mt = 0; mt < 4; ++mt) { ws4[mt] = (f32x4){0.f, 0.f, 0.f, 0.f}; qs4[mt] = ws4[mt]; }
; #pragma unroll
;                 for (int kc = 0; kc < 4; ++kc)
; #pragma unroll
;                     for (int mt = 0; mt < 4; ++mt) { ws4[mt] = MFMA16(wf[mt][kc], sb[kc], ws4[mt]); qs4[mt] = MFMA16(qf4[mt][kc], sb[kc], qs4[mt]); }
.LBB0_716:
	s_ashr_i32 s34, s42, 6
	s_lshr_b32 s12, s42, 3
	s_ashr_i32 s13, s42, 2
	s_ashr_i32 s35, s34, 31
	s_mov_b64 s[8:9], -1
	s_and_b64 vcc, exec, s[0:1]
	s_mul_hi_i32 s37, s34, 0x3000000
	s_mul_i32 s14, s34, 0x3000000
	s_barrier
	s_cbranch_vccz .LBB0_720
	s_setprio 3
	s_and_b32 s2, s41, 7
	s_and_b32 s6, s13, 8
	s_or_b32 s2, s6, s2
	s_and_b32 s2, s2, 15
	s_and_b32 s3, s12, 3
	s_lshl_b32 s2, s2, 8
	s_lshl_b32 s3, s3, 6
	s_waitcnt lgkmcnt(0)
	s_barrier
	s_or_b32 s2, s14, s2
	s_or_b32 s36, s2, s3
	s_waitcnt vmcnt(12)
	v_mov_b32_e32 v0, 0
	v_lshl_add_u64 v[202:203], v[200:201], 0, s[36:37]
	s_mov_b32 s8, 0
	s_mov_b64 s[38:39], 0
	v_mov_b32_e32 v1, v0
	v_mov_b32_e32 v2, v0
	v_mov_b32_e32 v3, v0
	s_waitcnt vmcnt(11)
	v_mov_b32_e32 v4, v0
	v_mov_b32_e32 v5, v0
	v_mov_b32_e32 v6, v0
	v_mov_b32_e32 v7, v0
	s_waitcnt vmcnt(10)
	v_mov_b32_e32 v8, v0
	v_mov_b32_e32 v9, v0
	v_mov_b32_e32 v10, v0
	v_mov_b32_e32 v11, v0
	s_waitcnt vmcnt(9)
	v_mov_b32_e32 v12, v0
	v_mov_b32_e32 v13, v0
	v_mov_b32_e32 v14, v0
	v_mov_b32_e32 v15, v0
	s_waitcnt vmcnt(8)
	v_mov_b32_e32 v16, v0
	v_mov_b32_e32 v17, v0
	v_mov_b32_e32 v18, v0
	v_mov_b32_e32 v19, v0
	s_waitcnt vmcnt(7)
	v_mov_b32_e32 v20, v0
	v_mov_b32_e32 v21, v0
	v_mov_b32_e32 v22, v0
	v_mov_b32_e32 v23, v0
	s_waitcnt vmcnt(6)
	v_mov_b32_e32 v24, v0
	v_mov_b32_e32 v25, v0
	v_mov_b32_e32 v26, v0
	v_mov_b32_e32 v27, v0
	s_waitcnt vmcnt(5)
	v_mov_b32_e32 v28, v0
	v_mov_b32_e32 v29, v0
	v_mov_b32_e32 v30, v0
	v_mov_b32_e32 v31, v0
	s_waitcnt vmcnt(0)
.LBB0_718:
	s_bitcmp1_b32 s8, 0
	s_cselect_b32 s2, 0x10900, 0
	s_add_i32 s2, s2, 16
	s_add_i32 s3, s2, 0x108fc
	v_add3_u32 v104, s2, v199, v242
	v_mov_b32_e32 v32, s3
	ds_read_b32 v179, v32
	ds_read2_b64 v[80:83], v104 offset1:4
	v_add_u32_e32 v32, 0x4000, v104
	v_add_u32_e32 v48, 0x1000, v104
	v_add_u32_e32 v49, 0x5000, v104
	v_add_u32_e32 v72, 0x2000, v104
	v_add_u32_e32 v73, 0x6000, v104
	v_add_u32_e32 v105, 0x3000, v104
	ds_read2_b64 v[84:87], v32 offset0:128 offset1:132
	ds_read2_b64 v[60:63], v104 offset0:8 offset1:12
	ds_read2_b64 v[56:59], v32 offset0:136 offset1:140
	ds_read2_b64 v[44:47], v104 offset0:16 offset1:20
	ds_read2_b64 v[40:43], v32 offset0:144 offset1:148
	ds_read2_b64 v[36:39], v104 offset0:24 offset1:28
	ds_read2_b64 v[32:35], v32 offset0:152 offset1:156
	ds_read2_b64 v[108:111], v48 offset0:32 offset1:36
	ds_read2_b64 v[116:119], v49 offset0:160 offset1:164
	ds_read2_b64 v[92:95], v48 offset0:40 offset1:44
	ds_read2_b64 v[88:91], v49 offset0:168 offset1:172
	ds_read2_b64 v[68:71], v48 offset0:48 offset1:52
	ds_read2_b64 v[64:67], v49 offset0:176 offset1:180
	ds_read2_b64 v[52:55], v48 offset0:56 offset1:60
	ds_read2_b64 v[48:51], v49 offset0:184 offset1:188
	ds_read2_b64 v[136:139], v72 offset0:64 offset1:68
	ds_read2_b64 v[140:143], v73 offset0:192 offset1:196
	ds_read2_b64 v[124:127], v72 offset0:72 offset1:76
	ds_read2_b64 v[120:123], v73 offset0:200 offset1:204
	ds_read2_b64 v[100:103], v72 offset0:80 offset1:84
	ds_read2_b64 v[96:99], v73 offset0:208 offset1:212
	ds_read2_b64 v[76:79], v72 offset0:88 offset1:92
	ds_read2_b64 v[72:75], v73 offset0:216 offset1:220
	ds_read2_b64 v[152:155], v105 offset0:96 offset1:100
	v_cvt_pk_bf16_f32 v204, v0, v1
	v_cvt_pk_bf16_f32 v205, v2, v3
	v_cvt_pk_bf16_f32 v206, v4, v5
	v_cvt_pk_bf16_f32 v207, v6, v7
	v_add_u32_e32 v104, 0x7000, v104
	ds_read2_b64 v[156:159], v104 offset0:224 offset1:228
	ds_read2_b64 v[148:151], v105 offset0:104 offset1:108
	ds_read2_b64 v[144:147], v104 offset0:232 offset1:236
	ds_read2_b64 v[132:135], v105 offset0:112 offset1:116
	ds_read2_b64 v[128:131], v104 offset0:240 offset1:244
	ds_read2_b64 v[112:115], v105 offset0:120 offset1:124
	ds_read2_b64 v[104:107], v104 offset0:248 offset1:252
	s_waitcnt lgkmcnt(14)
	v_mfma_f32_16x16x32_bf16 v[84:87], v[84:87], v[204:207], 0
	v_cvt_pk_bf16_f32 v208, v8, v9
	v_cvt_pk_bf16_f32 v209, v10, v11
	v_cvt_pk_bf16_f32 v210, v12, v13
	v_cvt_pk_bf16_f32 v211, v14, v15
	v_mfma_f32_16x16x32_bf16 v[80:83], v[80:83], v[204:207], 0
	v_cvt_pk_bf16_f32 v212, v16, v17
	v_cvt_pk_bf16_f32 v213, v18, v19
	v_cvt_pk_bf16_f32 v214, v20, v21
	v_mfma_f32_16x16x32_bf16 v[108:111], v[108:111], v[204:207], 0
	v_cvt_pk_bf16_f32 v215, v22, v23
	v_add3_u32 v183, s2, v243, v242
	v_cvt_pk_bf16_f32 v216, v24, v25
	s_waitcnt lgkmcnt(7)
	v_mfma_f32_16x16x32_bf16 v[152:155], v[152:155], v[204:207], 0
	v_cvt_pk_bf16_f32 v217, v26, v27
	v_cvt_pk_bf16_f32 v218, v28, v29
	v_cvt_pk_bf16_f32 v219, v30, v31
	v_mfma_f32_16x16x32_bf16 v[116:119], v[116:119], v[204:207], 0
	v_lshl_add_u32 v181, v244, 2, s2
	v_add3_u32 v193, s2, v245, v246
	s_waitcnt lgkmcnt(6)
	v_mfma_f32_16x16x32_bf16 v[156:159], v[156:159], v[204:207], 0
	v_add_u32_e32 v181, 0x10800, v181
	v_add_u32_e32 v195, 0xf400, v193
	s_mov_b32 s2, 0xe40a000
	v_mfma_f32_16x16x32_bf16 v[56:59], v[56:59], v[208:211], v[84:87]
	s_add_i32 s8, s8, 1
	v_mfma_f32_16x16x32_bf16 v[136:139], v[136:139], v[204:207], 0
	v_mfma_f32_16x16x32_bf16 v[140:143], v[140:143], v[204:207], 0
	v_mfma_f32_16x16x32_bf16 v[60:63], v[60:63], v[208:211], v[80:83]
	v_mfma_f32_16x16x32_bf16 v[80:83], v[92:95], v[208:211], v[108:111]
	s_waitcnt lgkmcnt(5)
	v_mfma_f32_16x16x32_bf16 v[108:111], v[148:151], v[208:211], v[152:155]
	v_mfma_f32_16x16x32_bf16 v[84:87], v[88:91], v[208:211], v[116:119]
	s_waitcnt lgkmcnt(4)
	v_mfma_f32_16x16x32_bf16 v[116:119], v[144:147], v[208:211], v[156:159]
	v_mfma_f32_16x16x32_bf16 v[40:43], v[40:43], v[212:215], v[56:59]
	v_mfma_f32_16x16x32_bf16 v[88:91], v[124:127], v[208:211], v[136:139]
	v_mfma_f32_16x16x32_bf16 v[92:95], v[120:123], v[208:211], v[140:143]
	v_mfma_f32_16x16x32_bf16 v[56:59], v[68:71], v[212:215], v[80:83]
	s_waitcnt lgkmcnt(3)
; #define LAS __attribute__((address_space(3)))
; __device__ __forceinline__ float bf2f(unsigned b) { return __uint_as_float(b << 16); }
; __device__ __forceinline__ void phase_dn_scan3(const Params& p, LAS unsigned char* lds) {
;     ...
;                 bf16x8 qkf[4][2], ktf[8][2];
; #pragma unroll
;                 for (int mt = 0; mt < 4; ++mt) { qkf[mt][0] = ldl44(qkr + 16 * mt * QP); qkf[mt][1] = ldl44(qkr + 16 * mt * QP + 64); }
; #pragma unroll
;                 for (int dt = 0; dt < 8; ++dt) { ktf[dt][0] = ldl44(ktr + 16 * dt * KP); ktf[dt][1] = ldl44(ktr + 16 * dt * KP + 64); }
;                 float gcv[4][4], uu[4][4];
; #pragma unroll
;                 for (int mt = 0; mt < 4; ++mt)
; #pragma unroll
;                     for (int r = 0; r < 4; ++r) { gcv[mt][r] = gcl[16 * mt + r]; uu[mt][r] = bf2f(*(const LAS bf16_t*)(ur + (16 * mt + r) * UP)); }
;                 asm volatile("" ::: "memory");
;                 f32x4 vn[4], vs[4], eg[4];
; #pragma unroll
;                 for (int mt = 0; mt < 4; ++mt)
; #pragma unroll
;                     for (int r = 0; r < 4; ++r) { eg[mt][r] = __expf(gcv[mt][r]); vn[mt][r] = uu[mt][r] - ws4[mt][r]; vs[mt][r] = vn[mt][r] * __expf(gl - gcv[mt][r]); }
	v_mfma_f32_16x16x32_bf16 v[80:83], v[132:135], v[212:215], v[108:111]
	v_mfma_f32_16x16x32_bf16 v[44:47], v[44:47], v[212:215], v[60:63]
	v_mfma_f32_16x16x32_bf16 v[60:63], v[64:67], v[212:215], v[84:87]
	s_waitcnt lgkmcnt(2)
	v_mfma_f32_16x16x32_bf16 v[84:87], v[128:131], v[212:215], v[116:119]
	v_mfma_f32_16x16x32_bf16 v[132:135], v[32:35], v[216:219], v[40:43]
	v_add_u32_e32 v32, 0xd000, v183
	ds_read2_b64 v[140:143], v32 offset1:4
	ds_read2_b64 v[136:139], v32 offset0:8 offset1:12
	v_add_u32_e32 v32, 0xd800, v183
	ds_read2_b64 v[128:131], v32 offset0:32 offset1:36
	ds_read2_b64 v[124:127], v32 offset0:40 offset1:44
	v_add_u32_e32 v32, 0xe000, v183
	v_mfma_f32_16x16x32_bf16 v[64:67], v[100:103], v[212:215], v[88:91]
	v_mfma_f32_16x16x32_bf16 v[68:71], v[96:99], v[212:215], v[92:95]
	s_waitcnt lgkmcnt(5)
	v_mfma_f32_16x16x32_bf16 v[230:233], v[112:115], v[216:219], v[80:83]
	ds_read2_b64 v[116:119], v32 offset0:64 offset1:68
	ds_read2_b64 v[112:115], v32 offset0:72 offset1:76
	v_add_u32_e32 v32, 0xe800, v183
	s_waitcnt lgkmcnt(6)
	v_mfma_f32_16x16x32_bf16 v[96:99], v[104:107], v[216:219], v[84:87]
	ds_read2_b64 v[104:107], v32 offset0:96 offset1:100
	ds_read2_b64 v[100:103], v32 offset0:104 offset1:108
	v_add_u32_e32 v32, 0x8800, v183
	ds_read2_b64 v[92:95], v32 offset1:4
	ds_read2_b64 v[88:91], v32 offset0:8 offset1:12
	v_add_u32_e32 v32, 0x9000, v183
	ds_read2_b64 v[84:87], v32 offset0:32 offset1:36
	ds_read2_b64 v[80:83], v32 offset0:40 offset1:44
	v_add_u32_e32 v32, 0x9800, v183
	v_mfma_f32_16x16x32_bf16 v[204:207], v[76:79], v[216:219], v[64:67]
	v_mfma_f32_16x16x32_bf16 v[108:111], v[72:75], v[216:219], v[68:71]
	ds_read2_b64 v[76:79], v32 offset0:64 offset1:68
	ds_read2_b64 v[72:75], v32 offset0:72 offset1:76
	v_add_u32_e32 v32, 0xa000, v183
	ds_read2_b64 v[68:71], v32 offset0:96 offset1:100
	ds_read2_b64 v[64:67], v32 offset0:104 offset1:108
	v_add_u32_e32 v32, 0xa800, v183
	v_mfma_f32_16x16x32_bf16 v[154:157], v[52:55], v[216:219], v[56:59]
	v_mfma_f32_16x16x32_bf16 v[120:123], v[48:51], v[216:219], v[60:63]
	s_nop 2
	ds_read2_b64 v[60:63], v32 offset0:128 offset1:132
	ds_read2_b64 v[56:59], v32 offset0:136 offset1:140
	v_add_u32_e32 v32, 0xb000, v183
	ds_read2_b64 v[52:55], v32 offset0:160 offset1:164
	ds_read2_b64 v[48:51], v32 offset0:168 offset1:172
	v_mfma_f32_16x16x32_bf16 v[146:149], v[36:39], v[216:219], v[44:47]
	v_add_u32_e32 v32, 0xb800, v183
	s_nop 1
	ds_read2_b64 v[44:47], v32 offset0:192 offset1:196
	ds_read2_b64 v[40:43], v32 offset0:200 offset1:204
	v_add_u32_e32 v32, 0xc000, v183
	ds_read2_b64 v[36:39], v32 offset0:224 offset1:228
	ds_read2_b64 v[32:35], v32 offset0:232 offset1:236
	ds_read_b128 v[150:153], v181
	ds_read_b128 v[208:211], v181 offset:64
	ds_read_b128 v[224:227], v181 offset:128
	ds_read_b128 v[234:237], v181 offset:192
	ds_read_u16 v158, v193 offset:62464
	ds_read_u16 v159, v193 offset:62544
	ds_read_u16 v181, v193 offset:62624
	ds_read_u16 v183, v193 offset:62704
	ds_read_u16 v214, v193 offset:63744
	ds_read_u16 v215, v193 offset:63824
	ds_read_u16 v222, v193 offset:63904
	ds_read_u16 v223, v193 offset:63984
	ds_read_u16 v228, v193 offset:65024
	ds_read_u16 v229, v193 offset:65104
	ds_read_u16 v238, v193 offset:65184
	ds_read_u16 v193, v193 offset:65264
	ds_read_u16 v239, v195 offset:3840
	ds_read_u16 v240, v195 offset:3920
	ds_read_u16 v241, v195 offset:4000
	ds_read_u16 v195, v195 offset:4080
	s_waitcnt lgkmcnt(14)
	v_mul_f32_e32 v144, 0x3fb8aa3b, v150
	v_mul_f32_e32 v145, 0x3fb8aa3b, v151
	v_exp_f32_e32 v216, v144
	v_sub_f32_e32 v144, v179, v150
	v_exp_f32_e32 v217, v145
	v_sub_f32_e32 v145, v179, v151
	v_lshlrev_b32_e32 v151, 16, v159
	v_lshlrev_b32_e32 v150, 16, v158
	v_pk_add_f32 v[146:147], v[150:151], v[146:147] neg_lo:[0,1] neg_hi:[0,1]
	v_mul_f32_e32 v150, 0x3fb8aa3b, v152
	v_exp_f32_e32 v218, v150
	v_sub_f32_e32 v150, v179, v152
	v_mul_f32_e32 v150, 0x3fb8aa3b, v150
	v_exp_f32_e32 v152, v150
	v_mul_f32_e32 v150, 0x3fb8aa3b, v153
	v_exp_f32_e32 v219, v150
	v_sub_f32_e32 v150, v179, v153
	v_mul_f32_e32 v150, 0x3fb8aa3b, v150
	v_exp_f32_e32 v153, v150
	s_waitcnt lgkmcnt(12)
	v_lshlrev_b32_e32 v151, 16, v183
	v_lshlrev_b32_e32 v150, 16, v181
	v_pk_add_f32 v[150:151], v[150:151], v[148:149] neg_lo:[0,1] neg_hi:[0,1]
	s_waitcnt lgkmcnt(10)
	v_lshlrev_b32_e32 v159, 16, v215
	v_pk_mul_f32 v[148:149], v[152:153], v[150:151]
	v_mul_f32_e32 v152, 0x3fb8aa3b, v208
	v_mul_f32_e32 v153, 0x3fb8aa3b, v209
	v_exp_f32_e32 v212, v152
	v_sub_f32_e32 v152, v179, v208
	v_exp_f32_e32 v213, v153
	v_sub_f32_e32 v153, v179, v209
	v_mul_f32_e32 v152, 0x3fb8aa3b, v152
	v_mul_f32_e32 v153, 0x3fb8aa3b, v153
	v_exp_f32_e32 v152, v152
	v_exp_f32_e32 v153, v153
	v_lshlrev_b32_e32 v158, 16, v214
	v_pk_add_f32 v[154:155], v[158:159], v[154:155] neg_lo:[0,1] neg_hi:[0,1]
	s_waitcnt lgkmcnt(8)
	v_lshlrev_b32_e32 v159, 16, v223
	v_pk_mul_f32 v[220:221], v[152:153], v[154:155]
	v_mul_f32_e32 v152, 0x3fb8aa3b, v210
	v_mul_f32_e32 v153, 0x3fb8aa3b, v211
	v_exp_f32_e32 v214, v152
	v_sub_f32_e32 v152, v179, v210
	v_exp_f32_e32 v215, v153
	v_sub_f32_e32 v153, v179, v211
	v_mul_f32_e32 v152, 0x3fb8aa3b, v152
	v_mul_f32_e32 v153, 0x3fb8aa3b, v153
	v_exp_f32_e32 v152, v152
	v_exp_f32_e32 v153, v153
	v_lshlrev_b32_e32 v158, 16, v222
	v_pk_add_f32 v[156:157], v[158:159], v[156:157] neg_lo:[0,1] neg_hi:[0,1]
	s_waitcnt lgkmcnt(6)
	v_lshlrev_b32_e32 v159, 16, v229
	v_pk_mul_f32 v[222:223], v[152:153], v[156:157]
	v_mul_f32_e32 v152, 0x3fb8aa3b, v224
	v_mul_f32_e32 v153, 0x3fb8aa3b, v225
	v_exp_f32_e32 v208, v152
	v_sub_f32_e32 v152, v179, v224
	v_exp_f32_e32 v209, v153
	v_sub_f32_e32 v153, v179, v225
	v_mul_f32_e32 v152, 0x3fb8aa3b, v152
	v_mul_f32_e32 v153, 0x3fb8aa3b, v153
	v_exp_f32_e32 v152, v152
	v_exp_f32_e32 v153, v153
	v_lshlrev_b32_e32 v158, 16, v228
	v_pk_add_f32 v[158:159], v[158:159], v[204:205] neg_lo:[0,1] neg_hi:[0,1]
	s_waitcnt lgkmcnt(4)
; __device__ __forceinline__ bf16_t f2bf(float f) { return (bf16_t)(cvt_pk_bf16(f, 0.f) & 0xffffu); }
; #define MFMA16(a, b, c) __builtin_amdgcn_mfma_f32_16x16x32_bf16((a), (b), (c), 0, 0, 0)
; __device__ __forceinline__ bf16x8 pack44(const f32x4 a, const f32x4 b) { u32x4 w = {pkbf(a[0], a[1]), pkbf(a[2], a[3]), pkbf(b[0], b[1]), pkbf(b[2], b[3])}; return __builtin_bit_cast(bf16x8, w); }
; __device__ __forceinline__ void phase_dn_scan3(const Params& p, LAS unsigned char* lds) {
;     ...
;                     for (int r = 0; r < 4; ++r) { eg[mt][r] = __expf(gcv[mt][r]); vn[mt][r] = uu[mt][r] - ws4[mt][r]; vs[mt][r] = vn[mt][r] * __expf(gl - gcv[mt][r]); }
;                 const bf16x8 vb10 = pack44(vn[0], vn[1]), vb11 = pack44(vn[2], vn[3]), vb20 = pack44(vs[0], vs[1]), vb21 = pack44(vs[2], vs[3]);
; #pragma unroll
;                 for (int mt = 0; mt < 4; ++mt) { f32x4 o = qs4[mt] * eg[mt];
;                     o = MFMA16(qkf[mt][0], vb10, o); o = MFMA16(qkf[mt][1], vb11, o);
; #pragma unroll
;                     for (int r = 0; r < 4; ++r) uo[(size_t)(16 * mt + r) * 6144] = f2bf(o[r]); }
	v_lshlrev_b32_e32 v205, 16, v193
	v_pk_mul_f32 v[224:225], v[152:153], v[158:159]
	v_mul_f32_e32 v152, 0x3fb8aa3b, v226
	v_mul_f32_e32 v153, 0x3fb8aa3b, v227
	v_exp_f32_e32 v210, v152
	v_sub_f32_e32 v152, v179, v226
	v_exp_f32_e32 v211, v153
	v_sub_f32_e32 v153, v179, v227
	v_mul_f32_e32 v152, 0x3fb8aa3b, v152
	v_mul_f32_e32 v153, 0x3fb8aa3b, v153
	v_exp_f32_e32 v152, v152
	v_exp_f32_e32 v153, v153
	v_lshlrev_b32_e32 v204, 16, v238
	v_pk_add_f32 v[228:229], v[204:205], v[206:207] neg_lo:[0,1] neg_hi:[0,1]
	s_waitcnt lgkmcnt(2)
	v_lshlrev_b32_e32 v207, 16, v240
	v_pk_mul_f32 v[226:227], v[152:153], v[228:229]
	v_mul_f32_e32 v152, 0x3fb8aa3b, v234
	v_mul_f32_e32 v153, 0x3fb8aa3b, v235
	v_exp_f32_e32 v204, v152
	v_sub_f32_e32 v152, v179, v234
	v_exp_f32_e32 v205, v153
	v_sub_f32_e32 v153, v179, v235
	v_mul_f32_e32 v152, 0x3fb8aa3b, v152
	v_mul_f32_e32 v153, 0x3fb8aa3b, v153
	v_lshlrev_b32_e32 v206, 16, v239
	v_mul_f32_e32 v181, 0x3fb8aa3b, v236
	v_exp_f32_e32 v152, v152
	v_exp_f32_e32 v153, v153
	v_pk_add_f32 v[230:231], v[206:207], v[230:231] neg_lo:[0,1] neg_hi:[0,1]
	v_exp_f32_e32 v206, v181
	v_sub_f32_e32 v181, v179, v236
	v_mul_f32_e32 v181, 0x3fb8aa3b, v181
	v_exp_f32_e32 v234, v181
	v_mul_f32_e32 v181, 0x3fb8aa3b, v237
	v_exp_f32_e32 v207, v181
	v_sub_f32_e32 v181, v179, v237
	s_waitcnt lgkmcnt(0)
	v_lshlrev_b32_e32 v237, 16, v195
	v_lshlrev_b32_e32 v236, 16, v241
	v_pk_add_f32 v[236:237], v[236:237], v[232:233] neg_lo:[0,1] neg_hi:[0,1]
	v_pk_mul_f32 v[232:233], v[152:153], v[230:231]
	v_cvt_pk_bf16_f32 v152, v146, v147
	v_cvt_pk_bf16_f32 v153, v150, v151
	v_cvt_pk_bf16_f32 v154, v154, v155
	v_cvt_pk_bf16_f32 v155, v156, v157
	v_pk_mul_f32 v[134:135], v[134:135], v[218:219]
	v_pk_mul_f32 v[132:133], v[132:133], v[216:217]
	v_cvt_pk_bf16_f32 v156, v158, v159
	v_cvt_pk_bf16_f32 v157, v228, v229
	v_mfma_f32_16x16x32_bf16 v[132:135], v[140:143], v[152:155], v[132:135]
	v_cvt_pk_bf16_f32 v158, v230, v231
	v_cvt_pk_bf16_f32 v159, v236, v237
	v_lshl_add_u64 v[238:239], v[202:203], 0, s[38:39]
	v_pk_mul_f32 v[122:123], v[122:123], v[214:215]
	v_mfma_f32_16x16x32_bf16 v[132:135], v[136:139], v[156:159], v[132:135]
	v_add_co_u32_e32 v136, vcc, s2, v238
	v_pk_mul_f32 v[120:121], v[120:121], v[212:213]
	s_nop 0
	v_addc_co_u32_e32 v137, vcc, 0, v239, vcc
	s_mov_b32 s2, 0xe40d000
	s_nop 2
	v_cvt_pk_bf16_f32 v132, v132, s0
	v_mfma_f32_16x16x32_bf16 v[120:123], v[128:131], v[152:155], v[120:123]
	global_store_short v[136:137], v132, off
	v_add_co_u32_e32 v132, vcc, s2, v238
	v_cvt_pk_bf16_f32 v136, v133, s0
	s_nop 0
	v_addc_co_u32_e32 v133, vcc, 0, v239, vcc
	s_mov_b32 s2, 0xe410000
	global_store_short v[132:133], v136, off
	v_add_co_u32_e32 v132, vcc, s2, v238
	v_cvt_pk_bf16_f32 v134, v134, s0
	s_nop 0
	v_addc_co_u32_e32 v133, vcc, 0, v239, vcc
	s_mov_b32 s2, 0xe413000
	v_mfma_f32_16x16x32_bf16 v[120:123], v[124:127], v[156:159], v[120:123]
	global_store_short v[132:133], v134, off
	v_add_co_u32_e32 v132, vcc, s2, v238
	s_mov_b32 s2, 0xe43a000
	s_nop 0
	v_addc_co_u32_e32 v133, vcc, 0, v239, vcc
	v_add_co_u32_e32 v124, vcc, s2, v238
	v_pk_mul_f32 v[110:111], v[110:111], v[210:211]
	v_pk_mul_f32 v[108:109], v[108:109], v[208:209]
	v_cvt_pk_bf16_f32 v120, v120, s0
	v_addc_co_u32_e32 v125, vcc, 0, v239, vcc
	s_mov_b32 s2, 0xe43d000
	v_mfma_f32_16x16x32_bf16 v[108:111], v[116:119], v[152:155], v[108:111]
	global_store_short v[124:125], v120, off
	v_add_co_u32_e32 v120, vcc, s2, v238
	v_cvt_pk_bf16_f32 v124, v121, s0
	s_nop 0
	v_addc_co_u32_e32 v121, vcc, 0, v239, vcc
	s_mov_b32 s2, 0xe440000
	global_store_short v[120:121], v124, off
	v_add_co_u32_e32 v120, vcc, s2, v238
	v_cvt_pk_bf16_f32 v122, v122, s0
	s_nop 0
	v_addc_co_u32_e32 v121, vcc, 0, v239, vcc
	s_mov_b32 s2, 0xe443000
	v_mfma_f32_16x16x32_bf16 v[108:111], v[112:115], v[156:159], v[108:111]
	global_store_short v[120:121], v122, off
	v_add_co_u32_e32 v120, vcc, s2, v238
	s_mov_b32 s2, 0xe46a000
	s_nop 0
	v_addc_co_u32_e32 v121, vcc, 0, v239, vcc
	v_add_co_u32_e32 v112, vcc, s2, v238
	v_pk_mul_f32 v[98:99], v[98:99], v[206:207]
	v_pk_mul_f32 v[96:97], v[96:97], v[204:205]
	v_cvt_pk_bf16_f32 v108, v108, s0
	v_addc_co_u32_e32 v113, vcc, 0, v239, vcc
	s_mov_b32 s2, 0xe46d000
	v_mfma_f32_16x16x32_bf16 v[96:99], v[104:107], v[152:155], v[96:99]
	global_store_short v[112:113], v108, off
; __device__ __forceinline__ bf16_t f2bf(float f) { return (bf16_t)(cvt_pk_bf16(f, 0.f) & 0xffffu); }
; #define MFMA16(a, b, c) __builtin_amdgcn_mfma_f32_16x16x32_bf16((a), (b), (c), 0, 0, 0)
; #define SC_BAR() do { asm volatile("s_waitcnt lgkmcnt(0)" ::: "memory"); __builtin_amdgcn_s_barrier(); asm volatile("" ::: "memory"); } while (0)
; __device__ __forceinline__ void phase_dn_scan3(const Params& p, LAS unsigned char* lds) {
;     ...
;                 for (int mt = 0; mt < 4; ++mt) { f32x4 o = qs4[mt] * eg[mt];
;                     o = MFMA16(qkf[mt][0], vb10, o); o = MFMA16(qkf[mt][1], vb11, o);
; #pragma unroll
;                     for (int r = 0; r < 4; ++r) uo[(size_t)(16 * mt + r) * 6144] = f2bf(o[r]); }
;                 const float egl = __expf(gl);
; #pragma unroll
;                 for (int dt = 0; dt < 8; ++dt) { f32x4 sn = S[dt] * egl; sn = MFMA16(ktf[dt][0], vb20, sn); sn = MFMA16(ktf[dt][1], vb21, sn); S[dt] = sn; }
;                 SC_BAR();
	v_add_co_u32_e32 v108, vcc, s2, v238
	v_cvt_pk_bf16_f32 v112, v109, s0
	s_nop 0
	v_addc_co_u32_e32 v109, vcc, 0, v239, vcc
	s_mov_b32 s2, 0xe470000
	global_store_short v[108:109], v112, off
	v_add_co_u32_e32 v108, vcc, s2, v238
	v_cvt_pk_bf16_f32 v110, v110, s0
	s_nop 0
	v_addc_co_u32_e32 v109, vcc, 0, v239, vcc
	s_mov_b32 s2, 0xe473000
	v_mfma_f32_16x16x32_bf16 v[96:99], v[100:103], v[156:159], v[96:99]
	global_store_short v[108:109], v110, off
	v_add_co_u32_e32 v108, vcc, s2, v238
	s_mov_b32 s2, 0xe49a000
	s_nop 0
	v_addc_co_u32_e32 v109, vcc, 0, v239, vcc
	v_add_co_u32_e32 v100, vcc, s2, v238
	s_nop 1
	v_cvt_pk_bf16_f32 v96, v96, s0
	v_addc_co_u32_e32 v101, vcc, 0, v239, vcc
	s_mov_b32 s2, 0xe49d000
	global_store_short v[100:101], v96, off
	v_add_co_u32_e32 v96, vcc, s2, v238
	v_cvt_pk_bf16_f32 v100, v97, s0
	s_nop 0
	v_addc_co_u32_e32 v97, vcc, 0, v239, vcc
	s_mov_b32 s2, 0xe4a0000
	global_store_short v[96:97], v100, off
	v_add_co_u32_e32 v96, vcc, s2, v238
	v_cvt_pk_bf16_f32 v98, v98, s0
	s_nop 0
	v_addc_co_u32_e32 v97, vcc, 0, v239, vcc
	s_mov_b32 s2, 0xe4a3000
	global_store_short v[96:97], v98, off
	v_add_co_u32_e32 v96, vcc, s2, v238
	v_mul_f32_e32 v144, 0x3fb8aa3b, v144
	v_mul_f32_e32 v145, 0x3fb8aa3b, v145
	v_cvt_pk_bf16_f32 v98, v99, s0
	v_addc_co_u32_e32 v97, vcc, 0, v239, vcc
	v_exp_f32_e32 v144, v144
	v_exp_f32_e32 v145, v145
	global_store_short v[96:97], v98, off
	v_mul_f32_e32 v96, 0x3fb8aa3b, v179
	v_exp_f32_e32 v96, v96
	v_mul_f32_e32 v181, 0x3fb8aa3b, v181
	v_pk_mul_f32 v[144:145], v[144:145], v[146:147]
	v_exp_f32_e32 v235, v181
	v_cvt_pk_bf16_f32 v144, v144, v145
	v_cvt_pk_bf16_f32 v145, v148, v149
	v_cvt_pk_bf16_f32 v146, v220, v221
	v_cvt_pk_bf16_f32 v147, v222, v223
	v_pk_mul_f32 v[2:3], v[2:3], v[96:97] op_sel_hi:[1,0]
	v_pk_mul_f32 v[0:1], v[0:1], v[96:97] op_sel_hi:[1,0]
	v_pk_mul_f32 v[6:7], v[6:7], v[96:97] op_sel_hi:[1,0]
	v_pk_mul_f32 v[4:5], v[4:5], v[96:97] op_sel_hi:[1,0]
	v_pk_mul_f32 v[10:11], v[10:11], v[96:97] op_sel_hi:[1,0]
	v_pk_mul_f32 v[8:9], v[8:9], v[96:97] op_sel_hi:[1,0]
	v_pk_mul_f32 v[14:15], v[14:15], v[96:97] op_sel_hi:[1,0]
	v_pk_mul_f32 v[12:13], v[12:13], v[96:97] op_sel_hi:[1,0]
	v_pk_mul_f32 v[18:19], v[18:19], v[96:97] op_sel_hi:[1,0]
	v_pk_mul_f32 v[16:17], v[16:17], v[96:97] op_sel_hi:[1,0]
	v_pk_mul_f32 v[22:23], v[22:23], v[96:97] op_sel_hi:[1,0]
	v_pk_mul_f32 v[20:21], v[20:21], v[96:97] op_sel_hi:[1,0]
	v_pk_mul_f32 v[26:27], v[26:27], v[96:97] op_sel_hi:[1,0]
	v_pk_mul_f32 v[24:25], v[24:25], v[96:97] op_sel_hi:[1,0]
	v_pk_mul_f32 v[30:31], v[30:31], v[96:97] op_sel_hi:[1,0]
	v_pk_mul_f32 v[28:29], v[28:29], v[96:97] op_sel_hi:[1,0]
	v_mfma_f32_16x16x32_bf16 v[0:3], v[92:95], v[144:147], v[0:3]
	v_mul_f32_e64 v234, v234, v236
	v_mul_f32_e64 v235, v235, v237
	v_cvt_pk_bf16_f32 v148, v224, v225
	v_cvt_pk_bf16_f32 v149, v226, v227
	v_mfma_f32_16x16x32_bf16 v[4:7], v[84:87], v[144:147], v[4:7]
	v_cvt_pk_bf16_f32 v150, v232, v233
	v_cvt_pk_bf16_f32 v151, v234, v235
	v_cvt_pk_bf16_f32 v134, v135, s0
	v_mfma_f32_16x16x32_bf16 v[8:11], v[76:79], v[144:147], v[8:11]
	v_cvt_pk_bf16_f32 v122, v123, s0
	v_cvt_pk_bf16_f32 v110, v111, s0
	global_store_short v[132:133], v134, off
	v_mfma_f32_16x16x32_bf16 v[12:15], v[68:71], v[144:147], v[12:15]
	global_store_short v[120:121], v122, off
	global_store_short v[108:109], v110, off
	s_waitcnt lgkmcnt(0)
	v_mfma_f32_16x16x32_bf16 v[16:19], v[60:63], v[144:147], v[16:19]
	s_barrier
	s_add_u32 s38, s38, 0xc0000
	v_mfma_f32_16x16x32_bf16 v[20:23], v[52:55], v[144:147], v[20:23]
	s_addc_u32 s39, s39, 0
	s_cmp_lg_u32 s38, 0x3000000
	v_mfma_f32_16x16x32_bf16 v[24:27], v[44:47], v[144:147], v[24:27]
	v_mfma_f32_16x16x32_bf16 v[28:31], v[36:39], v[144:147], v[28:31]
	v_mfma_f32_16x16x32_bf16 v[0:3], v[88:91], v[148:151], v[0:3]
	v_mfma_f32_16x16x32_bf16 v[4:7], v[80:83], v[148:151], v[4:7]
	v_mfma_f32_16x16x32_bf16 v[8:11], v[72:75], v[148:151], v[8:11]
	v_mfma_f32_16x16x32_bf16 v[12:15], v[64:67], v[148:151], v[12:15]
	v_mfma_f32_16x16x32_bf16 v[16:19], v[56:59], v[148:151], v[16:19]
	v_mfma_f32_16x16x32_bf16 v[20:23], v[48:51], v[148:151], v[20:23]
	v_mfma_f32_16x16x32_bf16 v[24:27], v[40:43], v[148:151], v[24:27]
	v_mfma_f32_16x16x32_bf16 v[28:31], v[32:35], v[148:151], v[28:31]
	s_cbranch_scc1 .LBB0_718
	s_setprio 0
	s_mov_b64 s[8:9], 0

; #define LAS __attribute__((address_space(3)))
; #define MFMA32(a, b, c) __builtin_amdgcn_mfma_f32_32x32x16_bf16((a), (b), (c), 0, 0, 0)
; __device__ __forceinline__ void phase_moba_mfma(const Params& p, LAS unsigned char* lds, unsigned lds_base) {
;     ...
;                 const LAS unsigned char* Ks = lds + OFF_K + buf * 64 * KST + i32 * KST + 16 * hh;
;                 f32x16 s0, s1;
; #pragma unroll
;                 for (int r = 0; r < 16; ++r) { s0[r] = 0.f; s1[r] = 0.f; }
; #pragma unroll
;                 for (int kc = 0; kc < 8; ++kc) { const bf16x8 a0 = *(const LAS bf16x8*)(Ks + 32 * kc), a1 = *(const LAS bf16x8*)(Ks + 32 * KST + 32 * kc);
;                     s0 = MFMA32(a0, qf[kc], s0); s1 = MFMA32(a1, qf[kc], s1); }
;                 const int tq = q0 + i32, kbase = j * 256 + kt * 64;
;                 const bool far = (q0 - (kbase + 63)) >= 790;
;                 const bool diag = own && (kbase + 63 > q0);
;                 const bool lsel = own || ((sel >> j) & 1u);
;                 const int db = tq - kbase - 4 * hh;
;                 if (far) {
; #pragma unroll
;                     for (int r = 0; r < 16; ++r) { s0[r] += c31; s1[r] += c31; }
;                 } else {
;                     const LAS float* bp = (const LAS float*)(lds + OFF_BT) + db;
;                     float b0[16], b1[16];
; #pragma unroll
;                     for (int r = 0; r < 16; ++r) { b0[r] = bp[-(8 * (r >> 2) + (r & 3))]; b1[r] = bp[-(32 + 8 * (r >> 2) + (r & 3))]; }
; #pragma unroll
;                     for (int r = 0; r < 16; ++r) { s0[r] += b0[r]; s1[r] += b1[r]; }
;                 }
;     ...
;                 const unsigned va = vbase + buf * 64 * VST;
;                 u32x2 v[8];
;                 { const bf16x8 pf = pack8(s0, 0); tr8<0, 8 * VST, 64>(va, v);
.LBB0_747:
	s_lshl_b32 s0, s19, 8
	s_lshl_b32 s1, s37, 6
	s_add_i32 s1, s1, s0
	s_or_b32 s4, s1, 63
	s_mul_i32 s0, s2, 0x4400
	v_add_u32_e32 v243, s0, v195
	s_mul_i32 s5, s2, 0x5000
	v_or_b32_e32 v1, s1, v180
	v_add_u32_e32 v242, s5, v207
	v_sub_u32_e32 v1, v218, v1
	s_sub_i32 s0, s6, s4
	s_cmpk_lt_i32 s0, 0x316
	s_cbranch_scc0 .Lmoba_far
	v_lshl_add_u32 v223, v1, 2, s3
	v_add_u32_e32 v223, 0xffffff14, v223
	ds_read2_b32 v[114:115], v223 offset0:59 offset1:58
	ds_read2_b32 v[98:99], v223 offset0:27 offset1:26
	ds_read2_b32 v[116:117], v223 offset0:57 offset1:56
	ds_read2_b32 v[100:101], v223 offset0:25 offset1:24
	ds_read2_b32 v[118:119], v223 offset0:51 offset1:50
	ds_read2_b32 v[102:103], v223 offset0:19 offset1:18
	ds_read2_b32 v[120:121], v223 offset0:49 offset1:48
	ds_read2_b32 v[104:105], v223 offset0:17 offset1:16
	ds_read2_b32 v[122:123], v223 offset0:43 offset1:42
	ds_read2_b32 v[106:107], v223 offset0:11 offset1:10
	ds_read2_b32 v[124:125], v223 offset0:41 offset1:40
	ds_read2_b32 v[108:109], v223 offset0:9 offset1:8
	ds_read2_b32 v[126:127], v223 offset0:35 offset1:34
	ds_read2_b32 v[110:111], v223 offset0:3 offset1:2
	ds_read2_b32 v[128:129], v223 offset0:33 offset1:32
	ds_read2_b32 v[112:113], v223 offset0:1 offset1:0
	v_mov_b32_e32 v251, 0
	ds_read_b128 v[66:69], v243 offset:0
	ds_read_b128 v[70:73], v243 offset:8704
	ds_read_b128 v[74:77], v243 offset:32
	ds_read_b128 v[78:81], v243 offset:8736
	ds_read_b128 v[82:85], v243 offset:64
	ds_read_b128 v[86:89], v243 offset:8768
	ds_read_b128 v[90:93], v243 offset:96
	ds_read_b128 v[94:97], v243 offset:8800
	s_waitcnt lgkmcnt(7)
	v_mfma_f32_32x32x16_bf16 v[114:129], v[66:69], v[130:133], v[114:129]
	ds_read_b128 v[66:69], v243 offset:128
	s_waitcnt lgkmcnt(7)
	v_mfma_f32_32x32x16_bf16 v[98:113], v[70:73], v[130:133], v[98:113]
	ds_read_b128 v[70:73], v243 offset:8832
	s_branch .Lmoba_scont
.Lmoba_far:
	v_mov_b32_e32 v251, v204
	ds_read_b128 v[66:69], v243 offset:0
	ds_read_b128 v[70:73], v243 offset:8704
	ds_read_b128 v[74:77], v243 offset:32
	ds_read_b128 v[78:81], v243 offset:8736
	ds_read_b128 v[82:85], v243 offset:64
	ds_read_b128 v[86:89], v243 offset:8768
	ds_read_b128 v[90:93], v243 offset:96
	ds_read_b128 v[94:97], v243 offset:8800
	s_waitcnt lgkmcnt(7)
	v_mfma_f32_32x32x16_bf16 v[114:129], v[66:69], v[130:133], 0
	ds_read_b128 v[66:69], v243 offset:128
	s_waitcnt lgkmcnt(7)
	v_mfma_f32_32x32x16_bf16 v[98:113], v[70:73], v[130:133], 0
	ds_read_b128 v[70:73], v243 offset:8832
.Lmoba_scont:
	s_waitcnt lgkmcnt(7)
	v_mfma_f32_32x32x16_bf16 v[114:129], v[74:77], v[134:137], v[114:129]
	ds_read_b128 v[74:77], v243 offset:160
	s_waitcnt lgkmcnt(7)
	v_mfma_f32_32x32x16_bf16 v[98:113], v[78:81], v[134:137], v[98:113]
	ds_read_b128 v[78:81], v243 offset:8864
	s_waitcnt lgkmcnt(7)
	v_mfma_f32_32x32x16_bf16 v[114:129], v[82:85], v[138:141], v[114:129]
	ds_read_b128 v[82:85], v243 offset:192
	s_waitcnt lgkmcnt(7)
	v_mfma_f32_32x32x16_bf16 v[98:113], v[86:89], v[138:141], v[98:113]
	ds_read_b128 v[86:89], v243 offset:8896
	s_waitcnt lgkmcnt(7)
	v_mfma_f32_32x32x16_bf16 v[114:129], v[90:93], v[142:145], v[114:129]
	ds_read_b128 v[90:93], v243 offset:224
	s_waitcnt lgkmcnt(7)
	v_mfma_f32_32x32x16_bf16 v[98:113], v[94:97], v[142:145], v[98:113]
	ds_read_b128 v[94:97], v243 offset:8928
	s_waitcnt lgkmcnt(7)
	v_mfma_f32_32x32x16_bf16 v[114:129], v[66:69], v[146:149], v[114:129]
	s_waitcnt lgkmcnt(6)
	v_mfma_f32_32x32x16_bf16 v[98:113], v[70:73], v[146:149], v[98:113]
	s_waitcnt lgkmcnt(5)
	v_mfma_f32_32x32x16_bf16 v[114:129], v[74:77], v[150:153], v[114:129]
	s_waitcnt lgkmcnt(4)
	v_mfma_f32_32x32x16_bf16 v[98:113], v[78:81], v[150:153], v[98:113]
	s_waitcnt lgkmcnt(3)
	v_mfma_f32_32x32x16_bf16 v[114:129], v[82:85], v[154:157], v[114:129]
	s_waitcnt lgkmcnt(2)
	v_mfma_f32_32x32x16_bf16 v[98:113], v[86:89], v[154:157], v[98:113]
	s_waitcnt lgkmcnt(1)
	v_mfma_f32_32x32x16_bf16 v[114:129], v[90:93], v[158:161], v[114:129]
	s_waitcnt lgkmcnt(0)
	v_mfma_f32_32x32x16_bf16 v[98:113], v[94:97], v[158:161], v[98:113]
	ds_read_b64_tr_b16 v[66:67], v242 offset:0
	ds_read_b64_tr_b16 v[68:69], v242 offset:2560
	ds_read_b64_tr_b16 v[70:71], v242 offset:64
	ds_read_b64_tr_b16 v[72:73], v242 offset:2624
	ds_read_b64_tr_b16 v[74:75], v242 offset:128
	ds_read_b64_tr_b16 v[76:77], v242 offset:2688
	ds_read_b64_tr_b16 v[78:79], v242 offset:192
	ds_read_b64_tr_b16 v[80:81], v242 offset:2752
	ds_read_b64_tr_b16 v[82:83], v242 offset:5120
	ds_read_b64_tr_b16 v[84:85], v242 offset:7680
	ds_read_b64_tr_b16 v[86:87], v242 offset:5184
	ds_read_b64_tr_b16 v[88:89], v242 offset:7744
	ds_read_b64_tr_b16 v[90:91], v242 offset:5248
	ds_read_b64_tr_b16 v[92:93], v242 offset:7808
	ds_read_b64_tr_b16 v[94:95], v242 offset:5312
	ds_read_b64_tr_b16 v[96:97], v242 offset:7872
	s_cmp_ge_i32 s6, s4
	s_cselect_b64 s[0:1], -1, 0
	s_xor_b64 s[4:5], s[16:17], -1
	s_or_b64 s[0:1], s[4:5], s[0:1]
	s_and_b64 vcc, exec, s[0:1]
	s_cbranch_vccnz .Lmoba_nodiag
; __device__ __forceinline__ void phase_moba_mfma(const Params& p, LAS unsigned char* lds, unsigned lds_base) {
;     ...
;                 if (diag) {
; #pragma unroll
;                     for (int r = 0; r < 16; ++r) { const int d0 = db - (8 * (r >> 2) + (r & 3)); if (d0 < 0) s0[r] = NINF; if (d0 < 32) s1[r] = NINF; }
;                 }
;                 float mx = NINF;
; #pragma unroll
;                 for (int r = 0; r < 16; ++r) { if (!lsel) { s0[r] = NINF; s1[r] = NINF; } mx = fmaxf(mx, fmaxf(s0[r], s1[r])); }
;                 mx = fmaxf(mx, __shfl_xor(mx, 32));
;                 const float mnew = fmaxf(m, mx);
;                 const float alpha = __builtin_amdgcn_exp2f(m - mnew);
;                 float ps = 0.f;
; #pragma unroll
;                 for (int r = 0; r < 16; ++r) { s0[r] = __builtin_amdgcn_exp2f(s0[r] - mnew); s1[r] = __builtin_amdgcn_exp2f(s1[r] - mnew); ps += s0[r] + s1[r]; }
;                 l = l * alpha + ps; m = mnew;
;                 if (__ballot(alpha != 1.0f) != 0ull) {
; #pragma unroll
;                     for (int dt = 0; dt < 4; ++dt)
; #pragma unroll
;                         for (int r = 0; r < 16; ++r) O[dt][r] *= alpha;
;                 }
	v_cmp_gt_i32_e64 s[4:5], 26, v1
	v_cmp_gt_i32_e32 vcc, 27, v1
	v_cmp_gt_i32_e64 s[96:97], 25, v1
	v_cmp_gt_i32_e64 s[94:95], 24, v1
	v_cndmask_b32_e32 v129, v129, v217, vcc
	s_and_b64 vcc, vcc, s[4:5]
	v_cndmask_b32_e32 v128, v128, v217, vcc
	s_and_b64 vcc, vcc, s[96:97]
	v_cmp_gt_i32_e64 s[92:93], 19, v1
	v_cndmask_b32_e32 v127, v127, v217, vcc
	s_and_b64 vcc, vcc, s[94:95]
	v_cmp_gt_i32_e64 s[90:91], 18, v1
	v_cndmask_b32_e32 v126, v126, v217, vcc
	s_and_b64 vcc, vcc, s[92:93]
	v_cmp_gt_i32_e64 s[88:89], 17, v1
	v_cndmask_b32_e32 v125, v125, v217, vcc
	s_and_b64 vcc, vcc, s[90:91]
	v_cmp_gt_i32_e64 s[86:87], 16, v1
	v_cndmask_b32_e32 v124, v124, v217, vcc
	s_and_b64 vcc, vcc, s[88:89]
	v_cmp_gt_i32_e64 s[84:85], 11, v1
	v_cndmask_b32_e32 v123, v123, v217, vcc
	s_and_b64 vcc, vcc, s[86:87]
	v_cmp_gt_i32_e64 s[82:83], 10, v1
	v_cndmask_b32_e32 v122, v122, v217, vcc
	s_and_b64 vcc, vcc, s[84:85]
	v_cmp_gt_i32_e64 s[80:81], 9, v1
	v_cndmask_b32_e32 v121, v121, v217, vcc
	s_and_b64 vcc, vcc, s[82:83]
	v_cmp_gt_i32_e64 s[78:79], 8, v1
	v_cndmask_b32_e32 v120, v120, v217, vcc
	s_and_b64 vcc, vcc, s[80:81]
	v_cmp_gt_i32_e64 s[76:77], 3, v1
	v_cndmask_b32_e32 v119, v119, v217, vcc
	s_and_b64 vcc, vcc, s[78:79]
	v_cmp_gt_i32_e64 s[74:75], 2, v1
	v_cndmask_b32_e32 v118, v118, v217, vcc
	s_and_b64 vcc, vcc, s[76:77]
	v_cmp_gt_i32_e64 s[72:73], 1, v1
	v_cndmask_b32_e32 v117, v117, v217, vcc
	s_and_b64 vcc, vcc, s[74:75]
	v_cmp_gt_i32_e64 s[66:67], 0, v1
	v_cndmask_b32_e32 v116, v116, v217, vcc
	s_and_b64 vcc, vcc, s[72:73]
	v_cndmask_b32_e32 v115, v115, v217, vcc
	s_and_b64 vcc, vcc, s[66:67]
	v_cmp_gt_i32_e64 s[64:65], 58, v1
	v_cndmask_b32_e32 v114, v114, v217, vcc
	v_cmp_gt_i32_e32 vcc, 59, v1
	v_cmp_gt_i32_e64 s[62:63], 57, v1
	v_cmp_gt_i32_e64 s[60:61], 56, v1
	v_cndmask_b32_e32 v113, v113, v217, vcc
	s_and_b64 vcc, vcc, s[64:65]
	v_cndmask_b32_e32 v112, v112, v217, vcc
	s_and_b64 vcc, vcc, s[62:63]
	v_cmp_gt_i32_e64 s[58:59], 51, v1
	v_cndmask_b32_e32 v111, v111, v217, vcc
	s_and_b64 vcc, vcc, s[60:61]
	v_cmp_gt_i32_e64 s[56:57], 50, v1
	v_cndmask_b32_e32 v110, v110, v217, vcc
	s_and_b64 vcc, vcc, s[58:59]
	v_cmp_gt_i32_e64 s[54:55], 49, v1
	v_cndmask_b32_e32 v109, v109, v217, vcc
	s_and_b64 vcc, vcc, s[56:57]
	v_cmp_gt_i32_e64 s[52:53], 48, v1
	v_cndmask_b32_e32 v108, v108, v217, vcc
	s_and_b64 vcc, vcc, s[54:55]
	v_cmp_gt_i32_e64 s[50:51], 43, v1
	v_cndmask_b32_e32 v107, v107, v217, vcc
	s_and_b64 vcc, vcc, s[52:53]
	v_cmp_gt_i32_e64 s[48:49], 42, v1
	v_cndmask_b32_e32 v106, v106, v217, vcc
	s_and_b64 vcc, vcc, s[50:51]
	v_cmp_gt_i32_e64 s[46:47], 41, v1
	v_cndmask_b32_e32 v105, v105, v217, vcc
	s_and_b64 vcc, vcc, s[48:49]
	v_cmp_gt_i32_e64 s[44:45], 40, v1
	v_cndmask_b32_e32 v104, v104, v217, vcc
	s_and_b64 vcc, vcc, s[46:47]
	v_cmp_gt_i32_e64 s[42:43], 35, v1
	v_cndmask_b32_e32 v103, v103, v217, vcc
	s_and_b64 vcc, vcc, s[44:45]
	v_cmp_gt_i32_e64 s[40:41], 34, v1
	v_cndmask_b32_e32 v102, v102, v217, vcc
	s_and_b64 vcc, vcc, s[42:43]
	v_cmp_gt_i32_e64 s[0:1], 33, v1
	v_cndmask_b32_e32 v101, v101, v217, vcc
	s_and_b64 vcc, vcc, s[40:41]
	v_cmp_gt_i32_e64 s[70:71], 32, v1
	v_cndmask_b32_e32 v100, v100, v217, vcc
	s_and_b64 vcc, vcc, s[0:1]
	v_cndmask_b32_e32 v99, v99, v217, vcc
	s_and_b64 vcc, vcc, s[70:71]
	v_cndmask_b32_e32 v98, v98, v217, vcc
.Lmoba_nodiag:
	s_lshl_b32 s0, 1, s19
	v_and_b32_e32 v1, s0, v201
	v_cmp_ne_u32_e32 vcc, 0, v1
	s_or_b64 s[0:1], s[16:17], vcc
	v_max3_f32 v221, v114, v115, v116
	v_max3_f32 v222, v98, v99, v100
	v_max3_f32 v221, v221, v117, v118
	v_max3_f32 v222, v222, v101, v102
	v_max3_f32 v221, v221, v119, v120
	v_max3_f32 v222, v222, v103, v104
	v_max3_f32 v221, v221, v121, v122
	v_max3_f32 v222, v222, v105, v106
	v_max3_f32 v221, v221, v123, v124
	v_max3_f32 v222, v222, v107, v108
	v_max3_f32 v221, v221, v125, v126
	v_max3_f32 v222, v222, v109, v110
	v_max3_f32 v221, v221, v127, v128
	v_max3_f32 v222, v222, v111, v112
	v_max_f32_e32 v221, v221, v129
	v_max_f32_e32 v222, v222, v113
	v_max_f32_e32 v221, v221, v222
	v_add_f32_e32 v221, v221, v251
	v_cndmask_b32_e64 v221, v217, v221, s[0:1]
	v_mov_b32_e32 v223, v221
	v_mov_b32_e32 v248, 0x7f800000
	s_nop 1
	v_permlane32_swap_b32_e32 v223, v221
	v_max3_f32 v249, v220, v221, v223
	v_sub_f32_e32 v250, v249, v220
	v_cmp_lt_f32_e32 vcc, 0x41000000, v250
	v_mov_b32_e32 v241, 0
	s_nop 1
	v_cndmask_b32_e32 v1, v220, v249, vcc
	s_cbranch_vccz .Lmoba_nors
	v_sub_f32_e32 v250, v220, v1
	v_exp_f32_e32 v244, v250
	s_nop 0
	v_mul_f32_e32 v219, v219, v244
	v_pk_mul_f32 v[2:3], v[2:3], v[244:245] op_sel_hi:[1,0]
	v_pk_mul_f32 v[4:5], v[4:5], v[244:245] op_sel_hi:[1,0]
	v_pk_mul_f32 v[6:7], v[6:7], v[244:245] op_sel_hi:[1,0]
	v_pk_mul_f32 v[8:9], v[8:9], v[244:245] op_sel_hi:[1,0]
	v_pk_mul_f32 v[10:11], v[10:11], v[244:245] op_sel_hi:[1,0]
	v_pk_mul_f32 v[12:13], v[12:13], v[244:245] op_sel_hi:[1,0]
	v_pk_mul_f32 v[14:15], v[14:15], v[244:245] op_sel_hi:[1,0]
	v_pk_mul_f32 v[16:17], v[16:17], v[244:245] op_sel_hi:[1,0]
	v_pk_mul_f32 v[18:19], v[18:19], v[244:245] op_sel_hi:[1,0]
	v_pk_mul_f32 v[20:21], v[20:21], v[244:245] op_sel_hi:[1,0]
	v_pk_mul_f32 v[22:23], v[22:23], v[244:245] op_sel_hi:[1,0]
	v_pk_mul_f32 v[24:25], v[24:25], v[244:245] op_sel_hi:[1,0]
	v_pk_mul_f32 v[26:27], v[26:27], v[244:245] op_sel_hi:[1,0]
	v_pk_mul_f32 v[28:29], v[28:29], v[244:245] op_sel_hi:[1,0]
	v_pk_mul_f32 v[30:31], v[30:31], v[244:245] op_sel_hi:[1,0]
	v_pk_mul_f32 v[32:33], v[32:33], v[244:245] op_sel_hi:[1,0]
	v_pk_mul_f32 v[34:35], v[34:35], v[244:245] op_sel_hi:[1,0]
	v_pk_mul_f32 v[36:37], v[36:37], v[244:245] op_sel_hi:[1,0]
	v_pk_mul_f32 v[38:39], v[38:39], v[244:245] op_sel_hi:[1,0]
	v_pk_mul_f32 v[40:41], v[40:41], v[244:245] op_sel_hi:[1,0]
	v_pk_mul_f32 v[42:43], v[42:43], v[244:245] op_sel_hi:[1,0]
	v_pk_mul_f32 v[44:45], v[44:45], v[244:245] op_sel_hi:[1,0]
	v_pk_mul_f32 v[46:47], v[46:47], v[244:245] op_sel_hi:[1,0]
	v_pk_mul_f32 v[48:49], v[48:49], v[244:245] op_sel_hi:[1,0]
	v_pk_mul_f32 v[50:51], v[50:51], v[244:245] op_sel_hi:[1,0]
	v_pk_mul_f32 v[52:53], v[52:53], v[244:245] op_sel_hi:[1,0]
	v_pk_mul_f32 v[54:55], v[54:55], v[244:245] op_sel_hi:[1,0]
	v_pk_mul_f32 v[56:57], v[56:57], v[244:245] op_sel_hi:[1,0]
	v_pk_mul_f32 v[58:59], v[58:59], v[244:245] op_sel_hi:[1,0]
	v_pk_mul_f32 v[60:61], v[60:61], v[244:245] op_sel_hi:[1,0]
	v_pk_mul_f32 v[62:63], v[62:63], v[244:245] op_sel_hi:[1,0]
	v_pk_mul_f32 v[64:65], v[64:65], v[244:245] op_sel_hi:[1,0]
; #define MFMA32(a, b, c) __builtin_amdgcn_mfma_f32_32x32x16_bf16((a), (b), (c), 0, 0, 0)
; __device__ __forceinline__ void phase_moba_mfma(const Params& p, LAS unsigned char* lds, unsigned lds_base) {
;     ...
;                 const float mnew = fmaxf(m, mx);
;                 const float alpha = __builtin_amdgcn_exp2f(m - mnew);
;                 float ps = 0.f;
; #pragma unroll
;                 for (int r = 0; r < 16; ++r) { s0[r] = __builtin_amdgcn_exp2f(s0[r] - mnew); s1[r] = __builtin_amdgcn_exp2f(s1[r] - mnew); ps += s0[r] + s1[r]; }
;                 l = l * alpha + ps; m = mnew;
;                 if (__ballot(alpha != 1.0f) != 0ull) {
; #pragma unroll
;                     for (int dt = 0; dt < 4; ++dt)
; #pragma unroll
;                         for (int r = 0; r < 16; ++r) O[dt][r] *= alpha;
;                 }
;                 const unsigned va = vbase + buf * 64 * VST;
;                 u32x2 v[8];
;                 { const bf16x8 pf = pack8(s0, 0); tr8<0, 8 * VST, 64>(va, v);
; #pragma unroll
;                   for (int dt = 0; dt < 4; ++dt) O[dt] = MFMA32(frag2(v[2 * dt], v[2 * dt + 1]), pf, O[dt]); }
;                 { const bf16x8 pf = pack8(s0, 1); tr8<16 * VST, 8 * VST, 64>(va, v);
; #pragma unroll
;                   for (int dt = 0; dt < 4; ++dt) O[dt] = MFMA32(frag2(v[2 * dt], v[2 * dt + 1]), pf, O[dt]); }
;                 { const bf16x8 pf = pack8(s1, 0); tr8<32 * VST, 8 * VST, 64>(va, v);
; #pragma unroll
;                   for (int dt = 0; dt < 4; ++dt) O[dt] = MFMA32(frag2(v[2 * dt], v[2 * dt + 1]), pf, O[dt]); }
;                 { const bf16x8 pf = pack8(s1, 1); tr8<48 * VST, 8 * VST, 64>(va, v);
; #pragma unroll
;                   for (int dt = 0; dt < 4; ++dt) O[dt] = MFMA32(frag2(v[2 * dt], v[2 * dt + 1]), pf, O[dt]); }
.Lmoba_nors:
	v_cndmask_b32_e64 v246, v248, v1, s[0:1]
	v_sub_f32_e32 v246, v246, v251
	v_sub_f32_e32 v114, v114, v246
	v_sub_f32_e32 v115, v115, v246
	v_sub_f32_e32 v116, v116, v246
	v_sub_f32_e32 v117, v117, v246
	v_sub_f32_e32 v118, v118, v246
	v_sub_f32_e32 v119, v119, v246
	v_sub_f32_e32 v120, v120, v246
	v_sub_f32_e32 v121, v121, v246
	v_exp_f32_e32 v114, v114
	v_exp_f32_e32 v115, v115
	v_exp_f32_e32 v116, v116
	v_exp_f32_e32 v117, v117
	v_exp_f32_e32 v118, v118
	v_exp_f32_e32 v119, v119
	v_exp_f32_e32 v120, v120
	v_exp_f32_e32 v121, v121
	v_add_f32_e32 v240, v114, v115
	v_add_f32_e32 v240, v240, v116
	v_add_f32_e32 v241, v241, v117
	v_add_f32_e32 v240, v240, v118
	v_add_f32_e32 v241, v241, v119
	v_add_f32_e32 v240, v240, v120
	v_add_f32_e32 v241, v241, v121
	v_cvt_pk_bf16_f32 v114, v114, v115
	v_cvt_pk_bf16_f32 v115, v116, v117
	v_cvt_pk_bf16_f32 v116, v118, v119
	v_cvt_pk_bf16_f32 v117, v120, v121
	v_sub_f32_e32 v122, v122, v246
	v_sub_f32_e32 v123, v123, v246
	s_waitcnt lgkmcnt(0)
	v_mfma_f32_32x32x16_bf16 v[50:65], v[66:69], v[114:117], v[50:65]
	v_mfma_f32_32x32x16_bf16 v[34:49], v[70:73], v[114:117], v[34:49]
	v_mfma_f32_32x32x16_bf16 v[18:33], v[74:77], v[114:117], v[18:33]
	v_mfma_f32_32x32x16_bf16 v[2:17], v[78:81], v[114:117], v[2:17]
	ds_read_b64_tr_b16 v[66:67], v242 offset:10240
	ds_read_b64_tr_b16 v[68:69], v242 offset:12800
	ds_read_b64_tr_b16 v[70:71], v242 offset:10304
	ds_read_b64_tr_b16 v[72:73], v242 offset:12864
	ds_read_b64_tr_b16 v[74:75], v242 offset:10368
	ds_read_b64_tr_b16 v[76:77], v242 offset:12928
	ds_read_b64_tr_b16 v[78:79], v242 offset:10432
	ds_read_b64_tr_b16 v[80:81], v242 offset:12992
	v_sub_f32_e32 v124, v124, v246
	v_sub_f32_e32 v125, v125, v246
	v_sub_f32_e32 v126, v126, v246
	v_sub_f32_e32 v127, v127, v246
	v_sub_f32_e32 v128, v128, v246
	v_sub_f32_e32 v129, v129, v246
	v_exp_f32_e32 v122, v122
	v_exp_f32_e32 v123, v123
	v_exp_f32_e32 v124, v124
	v_exp_f32_e32 v125, v125
	v_exp_f32_e32 v126, v126
	v_exp_f32_e32 v127, v127
	v_exp_f32_e32 v128, v128
	v_exp_f32_e32 v129, v129
	v_add_f32_e32 v240, v240, v122
	v_add_f32_e32 v241, v241, v123
	v_add_f32_e32 v240, v240, v124
	v_add_f32_e32 v241, v241, v125
	v_add_f32_e32 v240, v240, v126
	v_add_f32_e32 v241, v241, v127
	v_add_f32_e32 v240, v240, v128
	v_add_f32_e32 v241, v241, v129
	v_cvt_pk_bf16_f32 v118, v122, v123
	v_cvt_pk_bf16_f32 v119, v124, v125
	v_cvt_pk_bf16_f32 v120, v126, v127
	v_cvt_pk_bf16_f32 v121, v128, v129
	v_sub_f32_e32 v98, v98, v246
	v_sub_f32_e32 v99, v99, v246
	v_mfma_f32_32x32x16_bf16 v[50:65], v[82:85], v[118:121], v[50:65]
	v_mfma_f32_32x32x16_bf16 v[34:49], v[86:89], v[118:121], v[34:49]
	v_mfma_f32_32x32x16_bf16 v[18:33], v[90:93], v[118:121], v[18:33]
	v_mfma_f32_32x32x16_bf16 v[2:17], v[94:97], v[118:121], v[2:17]
	ds_read_b64_tr_b16 v[82:83], v242 offset:15360
	ds_read_b64_tr_b16 v[84:85], v242 offset:17920
	ds_read_b64_tr_b16 v[86:87], v242 offset:15424
	ds_read_b64_tr_b16 v[88:89], v242 offset:17984
	ds_read_b64_tr_b16 v[90:91], v242 offset:15488
	ds_read_b64_tr_b16 v[92:93], v242 offset:18048
	ds_read_b64_tr_b16 v[94:95], v242 offset:15552
	ds_read_b64_tr_b16 v[96:97], v242 offset:18112
	v_sub_f32_e32 v100, v100, v246
	v_sub_f32_e32 v101, v101, v246
	v_sub_f32_e32 v102, v102, v246
	v_sub_f32_e32 v103, v103, v246
	v_sub_f32_e32 v104, v104, v246
	v_sub_f32_e32 v105, v105, v246
	v_exp_f32_e32 v98, v98
	v_exp_f32_e32 v99, v99
	v_exp_f32_e32 v100, v100
	v_exp_f32_e32 v101, v101
	v_exp_f32_e32 v102, v102
	v_exp_f32_e32 v103, v103
	v_exp_f32_e32 v104, v104
	v_exp_f32_e32 v105, v105
	v_add_f32_e32 v240, v240, v98
	v_add_f32_e32 v241, v241, v99
	v_add_f32_e32 v240, v240, v100
	v_add_f32_e32 v241, v241, v101
	v_add_f32_e32 v240, v240, v102
	v_add_f32_e32 v241, v241, v103
	v_add_f32_e32 v240, v240, v104
	v_add_f32_e32 v241, v241, v105
	v_cvt_pk_bf16_f32 v98, v98, v99
	v_cvt_pk_bf16_f32 v99, v100, v101
	v_cvt_pk_bf16_f32 v100, v102, v103
	v_cvt_pk_bf16_f32 v101, v104, v105
	v_sub_f32_e32 v106, v106, v246
	v_sub_f32_e32 v107, v107, v246
	s_waitcnt lgkmcnt(8)
	v_mfma_f32_32x32x16_bf16 v[50:65], v[66:69], v[98:101], v[50:65]
	v_mfma_f32_32x32x16_bf16 v[34:49], v[70:73], v[98:101], v[34:49]
	v_mfma_f32_32x32x16_bf16 v[18:33], v[74:77], v[98:101], v[18:33]
	v_mfma_f32_32x32x16_bf16 v[2:17], v[78:81], v[98:101], v[2:17]
	v_sub_f32_e32 v108, v108, v246
	v_sub_f32_e32 v109, v109, v246
	v_sub_f32_e32 v110, v110, v246
	v_sub_f32_e32 v111, v111, v246
	v_sub_f32_e32 v112, v112, v246
	v_sub_f32_e32 v113, v113, v246
	v_exp_f32_e32 v106, v106
	v_exp_f32_e32 v107, v107
	v_exp_f32_e32 v108, v108
	v_exp_f32_e32 v109, v109
	v_exp_f32_e32 v110, v110
	v_exp_f32_e32 v111, v111
	v_exp_f32_e32 v112, v112
	v_exp_f32_e32 v113, v113
	v_add_f32_e32 v240, v240, v106
	v_add_f32_e32 v241, v241, v107
	v_add_f32_e32 v240, v240, v108
	v_add_f32_e32 v241, v241, v109
	v_add_f32_e32 v240, v240, v110
	v_add_f32_e32 v241, v241, v111
	v_add_f32_e32 v240, v240, v112
	v_add_f32_e32 v241, v241, v113
	v_cvt_pk_bf16_f32 v102, v106, v107
	v_cvt_pk_bf16_f32 v103, v108, v109
	v_cvt_pk_bf16_f32 v104, v110, v111
	v_cvt_pk_bf16_f32 v105, v112, v113
	v_add_f32_e32 v240, v240, v241
	v_add_f32_e32 v219, v219, v240
	s_waitcnt lgkmcnt(0)
	v_mfma_f32_32x32x16_bf16 v[50:65], v[82:85], v[102:105], v[50:65]
	v_mfma_f32_32x32x16_bf16 v[34:49], v[86:89], v[102:105], v[34:49]
	v_mfma_f32_32x32x16_bf16 v[18:33], v[90:93], v[102:105], v[18:33]
	v_mfma_f32_32x32x16_bf16 v[2:17], v[94:97], v[102:105], v[2:17]
	s_andn2_b64 vcc, exec, s[14:15]
	s_cbranch_vccz .LBB0_759
	s_branch .LBB0_760
